# scan chunk loop: 4 loop-invariant parameter quads loaded early into dead v[240:255] instead of right before use
# speedup vs baseline: 1.0396x; 1.0033x over previous
; DI float bflo(u32 v) { return __uint_as_float(v << 16); }
; __device__ __forceinline__ void scan_item(const Params& p, int stream, int h, unsigned char* smem) {
;     ...
;       const bool first = (t0 + et) == 0;
;       float rr[4], kk_[4], vv[4];
;       {
;         u32x2 c = g_cr, pv = first ? (u32x2){0u, 0u} : g_pr;
;         float cf[4] = {bflo(c[0]), bfhi(c[0]), bflo(c[1]), bfhi(c[1])};
;         float pf[4] = {bflo(pv[0]), bfhi(pv[0]), bflo(pv[1]), bfhi(pv[1])};
;         if (first && shift0) { float4 s4 = *(const float4*)(shift0 + hc); pf[0] = s4.x; pf[1] = s4.y; pf[2] = s4.z; pf[3] = s4.w; }
; #pragma unroll
;         for (int j = 0; j < 4; ++j) rr[j] = cf[j] + mu_r[j] * (pf[j] - cf[j]);
;       }
;       {
;         u32x2 c = g_ck, pv = first ? (u32x2){0u, 0u} : g_pk;
;         float cf[4] = {bflo(c[0]), bfhi(c[0]), bflo(c[1]), bfhi(c[1])};
;         float pf[4] = {bflo(pv[0]), bfhi(pv[0]), bflo(pv[1]), bfhi(pv[1])};
;         if (first && shift0) { float4 s4 = *(const float4*)(shift0 + 512 + hc); pf[0] = s4.x; pf[1] = s4.y; pf[2] = s4.z; pf[3] = s4.w; }
; #pragma unroll
;         for (int j = 0; j < 4; ++j) kk_[j] = cf[j] + mu_k[j] * (pf[j] - cf[j]);
;       }
;       {
;         u32x2 c = g_cv, pv = first ? (u32x2){0u, 0u} : g_pv;
;         float cf[4] = {bflo(c[0]), bfhi(c[0]), bflo(c[1]), bfhi(c[1])};
;         float pf[4] = {bflo(pv[0]), bfhi(pv[0]), bflo(pv[1]), bfhi(pv[1])};
;         if (first && shift0) { float4 s4 = *(const float4*)(shift0 + 1024 + hc); pf[0] = s4.x; pf[1] = s4.y; pf[2] = s4.z; pf[3] = s4.w; }
; #pragma unroll
;         for (int j = 0; j < 4; ++j) vv[j] = cf[j] + mu_v[j] * (pf[j] - cf[j]);
;       }
;       *(float4*)(sR + et * 64 + ec) = make_float4(rr[0], rr[1], rr[2], rr[3]);
;       *(float4*)(sKp + et * 64 + ec) = make_float4(kk_[0], kk_[1], kk_[2], kk_[3]);
;       *(float4*)(sV + et * 64 + ec) = make_float4(vv[0], vv[1], vv[2], vv[3]);
;       {
;         unsigned char* base; int kcol;
;         if (lseg < 64) { base = sTW; kcol = lseg; }
;         else if (lseg < 128) { base = sAL; kcol = lseg - 64; }
;         else { base = sSG; kcol = lseg - 128; }
;         const int st = kcol >> 5, c4 = (kcol & 31) >> 3;
; #pragma unroll
;         for (int hf = 0; hf < 2; ++hf) {
;           const u32x4 cc = hf ? g_cl1 : g_cl0;
;           u32x4 pq = {0u, 0u, 0u, 0u};
;           if (!first) pq = hf ? g_pl1 : g_pl0;
.LBB0_1589:
	s_or_b64 exec, exec, s[34:35]
	global_load_dwordx4 v[240:243], v[116:117], off
	global_load_dwordx4 v[244:247], v[116:117], off offset:16
	global_load_dwordx4 v[248:251], v[116:117], off offset:32
	global_load_dwordx4 v[252:255], v[116:117], off offset:48
	v_lshlrev_b32_e32 v0, 16, v104
	v_and_b32_e32 v1, 0xffff0000, v104
	v_lshlrev_b32_e32 v232, 16, v105
	v_and_b32_e32 v233, 0xffff0000, v105
	s_waitcnt vmcnt(4)
	v_pk_add_f32 v[84:85], v[84:85], v[0:1] neg_lo:[0,1] neg_hi:[0,1]
	v_cndmask_b32_e64 v3, v65, 0, vcc
	v_pk_fma_f32 v[80:81], v[80:81], v[84:85], v[0:1]
	v_pk_add_f32 v[0:1], v[86:87], v[232:233] neg_lo:[0,1] neg_hi:[0,1]
	v_lshlrev_b32_e32 v86, 16, v100
	v_and_b32_e32 v87, 0xffff0000, v100
	v_pk_fma_f32 v[82:83], v[82:83], v[0:1], v[232:233]
	v_lshlrev_b32_e32 v232, 16, v101
	v_and_b32_e32 v233, 0xffff0000, v101
	v_pk_add_f32 v[76:77], v[76:77], v[86:87] neg_lo:[0,1] neg_hi:[0,1]
	v_lshlrev_b32_e32 v0, 16, v106
	v_and_b32_e32 v1, 0xffff0000, v106
	v_lshlrev_b32_e32 v84, 16, v107
	v_and_b32_e32 v85, 0xffff0000, v107
	v_pk_fma_f32 v[72:73], v[72:73], v[76:77], v[86:87]
	v_pk_add_f32 v[76:77], v[78:79], v[232:233] neg_lo:[0,1] neg_hi:[0,1]
	v_pk_add_f32 v[78:79], v[90:91], v[84:85] neg_lo:[0,1] neg_hi:[0,1]
	v_pk_fma_f32 v[74:75], v[74:75], v[76:77], v[232:233]
	v_pk_add_f32 v[76:77], v[88:89], v[0:1] neg_lo:[0,1] neg_hi:[0,1]
	v_pk_fma_f32 v[70:71], v[70:71], v[78:79], v[84:85]
	v_pk_fma_f32 v[68:69], v[68:69], v[76:77], v[0:1]
	ds_write_b128 v197, v[72:75] offset:16384
	ds_write_b128 v197, v[80:83] offset:4096
	ds_write_b128 v197, v[68:71] offset:20480
	v_cndmask_b32_e64 v0, v67, 0, vcc
	v_cndmask_b32_e64 v1, v66, 0, vcc
	v_cndmask_b32_e64 v68, v64, 0, vcc
	v_lshlrev_b32_e32 v72, 16, v68
	v_and_b32_e32 v73, 0xffff0000, v68
	v_lshlrev_b32_e32 v74, 16, v3
	v_and_b32_e32 v75, 0xffff0000, v3
	v_lshlrev_b32_e32 v68, 16, v1
	v_and_b32_e32 v69, 0xffff0000, v1
	v_lshlrev_b32_e32 v70, 16, v0
	v_and_b32_e32 v71, 0xffff0000, v0
	s_and_saveexec_b64 s[34:35], s[0:1]
	s_cbranch_execz .LBB0_1591
	global_load_dwordx4 v[68:71], v[132:133], off offset:16
	global_load_dwordx4 v[72:75], v[132:133], off
.LBB0_1591:
	s_or_b64 exec, exec, s[34:35]


; DI float bflo(u32 v) { return __uint_as_float(v << 16); }
; DI float bfhi(u32 v) { return __uint_as_float(v & 0xffff0000u); }
; __device__ __forceinline__ void scan_item(const Params& p, int stream, int h, unsigned char* smem) {
;     ...
;           float cf[8], pf[8], lv[8];
; #pragma unroll
;           for (int j = 0; j < 4; ++j) {
;             cf[2 * j] = bflo(cc[j]); cf[2 * j + 1] = bfhi(cc[j]);
;             pf[2 * j] = bflo(pq[j]); pf[2 * j + 1] = bfhi(pq[j]);
;           }
;           if (first && shift0) {
; #pragma unroll
;             for (int j = 0; j < 8; ++j) pf[j] = shift0[1536 + lseg + hf * 8 + j];
;           }
;           const float4 m0 = *(const float4*)(mu + 1536 + lseg + hf * 8), m1 = *(const float4*)(mu + 1536 + lseg + hf * 8 + 4);
;           const float mul[8] = {m0.x, m0.y, m0.z, m0.w, m1.x, m1.y, m1.z, m1.w};
;           const float act_s = lseg < 64 ? 2.f : 1.f;
; #pragma unroll
;           for (int j = 0; j < 8; ++j) {
;             const float sft = cf[j] + mul[j] * (pf[j] - cf[j]);
	v_lshlrev_b32_e32 v0, 16, v56
	s_waitcnt vmcnt(0)
	v_sub_f32_e32 v72, v72, v0
	v_and_b32_e32 v1, 0xffff0000, v56
	v_lshlrev_b32_e32 v3, 16, v57
	v_and_b32_e32 v84, 0xffff0000, v57
	v_lshlrev_b32_e32 v85, 16, v58
	v_sub_f32_e32 v68, v68, v85
	v_and_b32_e32 v86, 0xffff0000, v58
	v_lshlrev_b32_e32 v87, 16, v59
	v_and_b32_e32 v88, 0xffff0000, v59

; __device__ __forceinline__ void scan_item(const Params& p, int stream, int h, unsigned char* smem) {
;     ...
;           for (int j = 0; j < 8; ++j) {
;             const float sft = cf[j] + mul[j] * (pf[j] - cf[j]);
	v_fmac_f32_e32 v85, v68, v244

; DI float frcp(float x) { return __builtin_amdgcn_rcpf(x); }
; __device__ __forceinline__ void scan_item(const Params& p, int stream, int h, unsigned char* smem) {
;     ...
;           if (first && shift0) {
; #pragma unroll
;             for (int j = 0; j < 8; ++j) pf[j] = shift0[1536 + lseg + hf * 8 + j];
;           }
;           const float4 m0 = *(const float4*)(mu + 1536 + lseg + hf * 8), m1 = *(const float4*)(mu + 1536 + lseg + hf * 8 + 4);
;           const float mul[8] = {m0.x, m0.y, m0.z, m0.w, m1.x, m1.y, m1.z, m1.w};
;           const float act_s = lseg < 64 ? 2.f : 1.f;
; #pragma unroll
;           for (int j = 0; j < 8; ++j) {
;             const float sft = cf[j] + mul[j] * (pf[j] - cf[j]);
;             const float sg = frcp(1.f + __expf(-act_s * sft));
;             lv[j] = lseg < 64 ? 2.f * sg - 1.f : (lseg >= 128 ? sg : sft);
;           }
;           u32x4 w0 = {pack2(lv[0], lv[1]), pack2(lv[2], lv[3]), pack2(lv[4], lv[5]), pack2(lv[6], lv[7])};
;           *(u32x4*)(base + (st << 10) + swz(et, c4 + hf)) = w0;
	v_fmac_f32_e32 v0, v72, v240
	v_mul_f32_e32 v72, v198, v0
	v_mul_f32_e32 v72, 0x3fb8aa3b, v72
	v_exp_f32_e32 v72, v72
	v_mul_f32_e32 v68, v198, v85
	v_mul_f32_e32 v68, 0x3fb8aa3b, v68
	v_exp_f32_e32 v68, v68
	v_add_f32_e32 v72, 1.0, v72
	v_rcp_f32_e32 v72, v72
	v_add_f32_e32 v68, 1.0, v68
	v_rcp_f32_e32 v68, v68
	v_fma_f32 v80, v72, 2.0, -1.0
	v_cndmask_b32_e64 v0, v0, v72, s[4:5]
	v_sub_f32_e32 v72, v73, v1
	v_fmac_f32_e32 v1, v72, v241
	v_mul_f32_e32 v72, v198, v1
	v_mul_f32_e32 v72, 0x3fb8aa3b, v72
	v_exp_f32_e32 v72, v72
	v_cndmask_b32_e64 v0, v0, v80, s[2:3]
	v_add_f32_e32 v72, 1.0, v72
	v_rcp_f32_e32 v72, v72
	s_nop 0
	v_fma_f32 v73, v72, 2.0, -1.0
	v_cndmask_b32_e64 v1, v1, v72, s[4:5]
	v_sub_f32_e32 v72, v74, v3
	v_fmac_f32_e32 v3, v72, v242
	v_mul_f32_e32 v72, v198, v3
	v_mul_f32_e32 v72, 0x3fb8aa3b, v72
	v_exp_f32_e32 v72, v72
	v_cndmask_b32_e64 v1, v1, v73, s[2:3]
	v_add_f32_e32 v72, 1.0, v72
	v_rcp_f32_e32 v72, v72
	s_nop 0
	v_fma_f32 v73, v72, 2.0, -1.0
	v_cndmask_b32_e64 v3, v3, v72, s[4:5]
	v_sub_f32_e32 v72, v75, v84
	v_fmac_f32_e32 v84, v72, v243
	v_mul_f32_e32 v72, v198, v84
	v_mul_f32_e32 v72, 0x3fb8aa3b, v72
	v_exp_f32_e32 v72, v72
	v_cndmask_b32_e64 v3, v3, v73, s[2:3]
	v_add_f32_e32 v72, 1.0, v72
	v_rcp_f32_e32 v72, v72
	s_nop 0
	v_fma_f32 v73, v72, 2.0, -1.0
	v_cndmask_b32_e64 v72, v84, v72, s[4:5]
	v_cndmask_b32_e64 v72, v72, v73, s[2:3]
	v_fma_f32 v73, v68, 2.0, -1.0
	v_cndmask_b32_e64 v68, v85, v68, s[4:5]
	v_cndmask_b32_e64 v73, v68, v73, s[2:3]
	v_sub_f32_e32 v68, v69, v86
	v_fmac_f32_e32 v86, v68, v245
	v_mul_f32_e32 v68, v198, v86
	v_mul_f32_e32 v68, 0x3fb8aa3b, v68
	v_exp_f32_e32 v68, v68
	s_nop 0
	v_add_f32_e32 v68, 1.0, v68
	v_rcp_f32_e32 v68, v68
	s_nop 0
	v_fma_f32 v69, v68, 2.0, -1.0
	v_cndmask_b32_e64 v68, v86, v68, s[4:5]
	v_cndmask_b32_e64 v74, v68, v69, s[2:3]
	v_sub_f32_e32 v68, v70, v87
	v_fmac_f32_e32 v87, v68, v246
	v_mul_f32_e32 v68, v198, v87
	v_mul_f32_e32 v68, 0x3fb8aa3b, v68
	v_exp_f32_e32 v68, v68
	v_cvt_pk_bf16_f32 v70, v73, v74
	v_add_f32_e32 v68, 1.0, v68
	v_rcp_f32_e32 v68, v68
	s_nop 0
	v_fma_f32 v69, v68, 2.0, -1.0
	v_cndmask_b32_e64 v68, v87, v68, s[4:5]
	v_cndmask_b32_e64 v75, v68, v69, s[2:3]
	v_sub_f32_e32 v68, v71, v88
	v_fmac_f32_e32 v88, v68, v247
	v_mul_f32_e32 v68, v198, v88
	v_mul_f32_e32 v68, 0x3fb8aa3b, v68
	v_exp_f32_e32 v68, v68
	s_nop 0
	v_add_f32_e32 v68, 1.0, v68
	v_rcp_f32_e32 v68, v68
	s_nop 0
	v_fma_f32 v69, v68, 2.0, -1.0
	v_cndmask_b32_e64 v68, v88, v68, s[4:5]
	v_cndmask_b32_e64 v71, v68, v69, s[2:3]
	v_cvt_pk_bf16_f32 v68, v0, v1
	v_cvt_pk_bf16_f32 v69, v3, v72
	v_cvt_pk_bf16_f32 v71, v75, v71
	ds_write_b128 v219, v[68:71]
	v_cndmask_b32_e64 v0, v63, 0, vcc
	v_cndmask_b32_e64 v1, v62, 0, vcc
	v_cndmask_b32_e64 v3, v61, 0, vcc
	v_cndmask_b32_e64 v69, v60, 0, vcc
	v_lshlrev_b32_e32 v68, 16, v69
	v_and_b32_e32 v69, 0xffff0000, v69
	v_lshlrev_b32_e32 v70, 16, v3
	v_and_b32_e32 v71, 0xffff0000, v3
	v_lshlrev_b32_e32 v72, 16, v1
	v_and_b32_e32 v73, 0xffff0000, v1
	v_lshlrev_b32_e32 v74, 16, v0
	v_and_b32_e32 v75, 0xffff0000, v0
	s_and_saveexec_b64 s[34:35], s[0:1]
	s_cbranch_execz .LBB0_1593
	global_load_dwordx4 v[72:75], v[134:135], off offset:16
	global_load_dwordx4 v[68:71], v[134:135], off
.LBB0_1593:
	s_or_b64 exec, exec, s[34:35]


; DI float bflo(u32 v) { return __uint_as_float(v << 16); }
; DI float bfhi(u32 v) { return __uint_as_float(v & 0xffff0000u); }
; __device__ __forceinline__ void scan_item(const Params& p, int stream, int h, unsigned char* smem) {
;     ...
;           float cf[8], pf[8], lv[8];
; #pragma unroll
;           for (int j = 0; j < 4; ++j) {
;             cf[2 * j] = bflo(cc[j]); cf[2 * j + 1] = bfhi(cc[j]);
;             pf[2 * j] = bflo(pq[j]); pf[2 * j + 1] = bfhi(pq[j]);
;           }
;           if (first && shift0) {
; #pragma unroll
;             for (int j = 0; j < 8; ++j) pf[j] = shift0[1536 + lseg + hf * 8 + j];
;           }
;           const float4 m0 = *(const float4*)(mu + 1536 + lseg + hf * 8), m1 = *(const float4*)(mu + 1536 + lseg + hf * 8 + 4);
;           const float mul[8] = {m0.x, m0.y, m0.z, m0.w, m1.x, m1.y, m1.z, m1.w};
;           const float act_s = lseg < 64 ? 2.f : 1.f;
; #pragma unroll
;           for (int j = 0; j < 8; ++j) {
;             const float sft = cf[j] + mul[j] * (pf[j] - cf[j]);
	v_lshlrev_b32_e32 v0, 16, v52
	v_and_b32_e32 v1, 0xffff0000, v52
	v_lshlrev_b32_e32 v3, 16, v53
	v_and_b32_e32 v84, 0xffff0000, v53
	v_lshlrev_b32_e32 v85, 16, v54
	v_and_b32_e32 v86, 0xffff0000, v54
	v_lshlrev_b32_e32 v87, 16, v55
	v_and_b32_e32 v88, 0xffff0000, v55
	s_waitcnt vmcnt(0)
	v_sub_f32_e32 v68, v68, v0
	v_sub_f32_e32 v69, v69, v1
	v_sub_f32_e32 v70, v70, v3
	v_sub_f32_e32 v71, v71, v84
	v_sub_f32_e32 v72, v72, v85
	v_sub_f32_e32 v73, v73, v86
	v_sub_f32_e32 v74, v74, v87
	v_sub_f32_e32 v75, v75, v88
	s_add_i32 s74, s66, 32
	s_cmp_ge_u32 s74, s40
	s_cselect_b64 s[60:61], -1, 0
	s_and_b64 vcc, exec, s[60:61]

; __device__ __forceinline__ void scan_item(const Params& p, int stream, int h, unsigned char* smem) {
;     ...
;           for (int j = 0; j < 8; ++j) {
;             const float sft = cf[j] + mul[j] * (pf[j] - cf[j]);
	v_fmac_f32_e32 v0, v68, v248
	v_fmac_f32_e32 v1, v69, v249
	v_fmac_f32_e32 v3, v70, v250
	v_fmac_f32_e32 v84, v71, v251

; DI float frcp(float x) { return __builtin_amdgcn_rcpf(x); }
; __device__ __forceinline__ void scan_item(const Params& p, int stream, int h, unsigned char* smem) {
;     ...
; #pragma unroll
;           for (int j = 0; j < 8; ++j) {
;             const float sft = cf[j] + mul[j] * (pf[j] - cf[j]);
;             const float sg = frcp(1.f + __expf(-act_s * sft));
;             lv[j] = lseg < 64 ? 2.f * sg - 1.f : (lseg >= 128 ? sg : sft);
;           }
;           u32x4 w0 = {pack2(lv[0], lv[1]), pack2(lv[2], lv[3]), pack2(lv[4], lv[5]), pack2(lv[6], lv[7])};
;           *(u32x4*)(base + (st << 10) + swz(et, c4 + hf)) = w0;
;         }
;       }
;       if (tb + 32 < T) SCAN_LOAD(t0 + 32);
	v_fmac_f32_e32 v85, v72, v252
	v_fmac_f32_e32 v86, v73, v253
	v_fmac_f32_e32 v87, v74, v254
	v_fmac_f32_e32 v88, v75, v255
	v_mul_f32_e32 v68, v198, v0
	v_mul_f32_e32 v69, v198, v1
	v_mul_f32_e32 v70, v198, v3
	v_mul_f32_e32 v71, v198, v84
	v_mul_f32_e32 v72, v198, v85
	v_mul_f32_e32 v73, v198, v86
	v_mul_f32_e32 v74, v198, v87
	v_mul_f32_e32 v75, v198, v88
	v_mul_f32_e32 v68, 0x3fb8aa3b, v68
	v_mul_f32_e32 v69, 0x3fb8aa3b, v69
	v_mul_f32_e32 v70, 0x3fb8aa3b, v70
	v_mul_f32_e32 v71, 0x3fb8aa3b, v71
	v_mul_f32_e32 v72, 0x3fb8aa3b, v72
	v_mul_f32_e32 v73, 0x3fb8aa3b, v73
	v_mul_f32_e32 v74, 0x3fb8aa3b, v74
	v_mul_f32_e32 v75, 0x3fb8aa3b, v75
	v_exp_f32_e32 v68, v68
	v_exp_f32_e32 v69, v69
	v_exp_f32_e32 v70, v70
	v_exp_f32_e32 v71, v71
	v_exp_f32_e32 v72, v72
	v_exp_f32_e32 v73, v73
	v_exp_f32_e32 v74, v74
	v_exp_f32_e32 v75, v75
	v_add_f32_e32 v68, 1.0, v68
	v_add_f32_e32 v69, 1.0, v69
	v_add_f32_e32 v70, 1.0, v70
	v_add_f32_e32 v71, 1.0, v71
	v_add_f32_e32 v72, 1.0, v72
	v_add_f32_e32 v73, 1.0, v73
	v_add_f32_e32 v74, 1.0, v74
	v_add_f32_e32 v75, 1.0, v75
	v_rcp_f32_e32 v68, v68
	v_rcp_f32_e32 v69, v69
	v_rcp_f32_e32 v70, v70
	v_rcp_f32_e32 v71, v71
	v_rcp_f32_e32 v72, v72
	v_rcp_f32_e32 v73, v73
	v_rcp_f32_e32 v74, v74
	v_rcp_f32_e32 v75, v75
	v_fma_f32 v76, v68, 2.0, -1.0
	v_cndmask_b32_e64 v0, v0, v68, s[4:5]
	v_fma_f32 v68, v69, 2.0, -1.0
	v_cndmask_b32_e64 v1, v1, v69, s[4:5]
	v_fma_f32 v69, v70, 2.0, -1.0
	v_cndmask_b32_e64 v3, v3, v70, s[4:5]
	v_fma_f32 v70, v71, 2.0, -1.0
	v_cndmask_b32_e64 v71, v84, v71, s[4:5]
	v_fma_f32 v77, v72, 2.0, -1.0
	v_cndmask_b32_e64 v72, v85, v72, s[4:5]
	v_fma_f32 v78, v73, 2.0, -1.0
	v_cndmask_b32_e64 v73, v86, v73, s[4:5]
	v_fma_f32 v79, v74, 2.0, -1.0
	v_cndmask_b32_e64 v74, v87, v74, s[4:5]
	v_fma_f32 v80, v75, 2.0, -1.0
	v_cndmask_b32_e64 v75, v88, v75, s[4:5]
	v_cndmask_b32_e64 v0, v0, v76, s[2:3]
	v_cndmask_b32_e64 v1, v1, v68, s[2:3]
	v_cndmask_b32_e64 v3, v3, v69, s[2:3]
	v_cndmask_b32_e64 v69, v71, v70, s[2:3]
	v_cndmask_b32_e64 v70, v72, v77, s[2:3]
	v_cndmask_b32_e64 v71, v73, v78, s[2:3]
	v_cndmask_b32_e64 v72, v74, v79, s[2:3]
	v_cndmask_b32_e64 v73, v75, v80, s[2:3]
	v_cvt_pk_bf16_f32 v68, v0, v1
	v_cvt_pk_bf16_f32 v69, v3, v69
	v_cvt_pk_bf16_f32 v70, v70, v71
	v_cvt_pk_bf16_f32 v71, v72, v73
	ds_write_b128 v220, v[68:71]
	s_cbranch_vccnz .LBB0_1595
	v_add_u32_e32 v0, 32, v170
	v_ashrrev_i32_e32 v1, 31, v0
	v_lshl_add_u64 v[0:1], v[124:125], 0, v[0:1]
	v_cmp_gt_i64_e32 vcc, s[48:49], v[0:1]
	v_mov_b64_e32 v[52:53], s[24:25]
	v_mov_b32_e32 v167, v2
	v_cndmask_b32_e32 v56, v184, v0, vcc
	v_mad_u64_u32 v[52:53], s[0:1], v56, s94, v[52:53]
	v_cndmask_b32_e32 v3, 0, v1, vcc
	v_mov_b32_e32 v54, v53
	v_mad_u64_u32 v[54:55], s[0:1], v3, s94, v[54:55]
	v_mov_b32_e32 v53, v54
	v_mov_b64_e32 v[54:55], s[50:51]
	v_mad_u64_u32 v[54:55], s[0:1], v56, s95, v[54:55]
	v_mov_b32_e32 v56, v55
	v_mad_u64_u32 v[56:57], s[0:1], v3, s95, v[56:57]
	v_cmp_lt_i64_e32 vcc, 0, v[0:1]
	v_mov_b32_e32 v169, v2
	s_nop 0
	v_cndmask_b32_e32 v1, 0, v56, vcc
	v_cndmask_b32_e32 v0, 0, v54, vcc
	v_lshl_add_u64 v[0:1], v[0:1], 1, s[24:25]
	v_lshl_add_u64 v[54:55], v[52:53], 0, v[166:167]
	v_lshl_add_u64 v[56:57], v[0:1], 0, v[166:167]
	global_load_dwordx2 v[100:101], v[54:55], off
	global_load_dwordx2 v[102:103], v[56:57], off
	global_load_dwordx2 v[104:105], v[54:55], off offset:1024
	global_load_dwordx2 v[106:107], v[54:55], off offset:2048
	global_load_dwordx2 v[108:109], v[56:57], off offset:1024
	global_load_dwordx2 v[110:111], v[56:57], off offset:2048
	v_lshl_add_u64 v[56:57], v[52:53], 0, v[168:169]
	v_lshl_add_u64 v[0:1], v[0:1], 0, v[168:169]
	global_load_dwordx4 v[52:55], v[56:57], off offset:3088
	s_nop 0
	global_load_dwordx4 v[56:59], v[56:57], off offset:3072
	s_nop 0
	global_load_dwordx4 v[60:63], v[0:1], off offset:3088
	global_load_dwordx4 v[64:67], v[0:1], off offset:3072
